# v76 + P2 k-tile epilogue row-norm sums via permlane16/32 swaps instead of ds_bpermute
# baseline (speedup 1.0000x reference)
;     __device__ __forceinline__ void operator()(const f32x4 (&acc)[2][2][4][2], const Unit& u, int wr, int wc, int fr, int fq) const {
;     ...
;             for (int bj = 0; bj < 2; ++bj) { float mx = 0.f;
; #pragma unroll
;                 for (int ai = 0; ai < 2; ++ai)
; #pragma unroll
;                     for (int m = 0; m < 4; ++m) { const f32x4 a = acc[ai][bj][m][0], c = acc[ai][bj][m][1];
;                         float s = (a[0] * a[0] + a[1] * a[1]) + (a[2] * a[2] + a[3] * a[3]) + (c[0] * c[0] + c[1] * c[1]) + (c[2] * c[2] + c[3] * c[3]);
;                         s += __builtin_bit_cast(float, __builtin_amdgcn_ds_bpermute((lane ^ 16) << 2, __builtin_bit_cast(int, s)));
;                         s += __builtin_bit_cast(float, __builtin_amdgcn_ds_bpermute((lane ^ 32) << 2, __builtin_bit_cast(int, s)));
;                         mx = fmaxf(mx, s); }
; #pragma unroll
;                 for (int x = 1; x < 16; x <<= 1) mx = fmaxf(mx, __builtin_bit_cast(float, __builtin_amdgcn_ds_bpermute((lane ^ x) << 2, __builtin_bit_cast(int, mx))));
;                 if (lane == 0) atomicMax(nrmk + (((u.pm >> 3) * 8 + 2 * (pn - 4) + bj) * 2 + (wc >> 1)) * 2 + (wc & 1), __float_as_uint(mx)); }
.LBB0_204:
	v_mul_f32_e32 v146, v125, v125
	v_mul_f32_e32 v147, v127, v127
	v_fmac_f32_e32 v146, v124, v124
	v_fmac_f32_e32 v147, v126, v126
	v_add_f32_e32 v146, v146, v147
	v_mul_f32_e32 v147, v121, v121
	v_fmac_f32_e32 v147, v120, v120
	v_add_f32_e32 v146, v146, v147
	v_mul_f32_e32 v147, v123, v123
	v_fmac_f32_e32 v147, v122, v122
	v_add_f32_e32 v146, v147, v146
	v_mul_f32_e32 v148, v119, v119
	v_fmac_f32_e32 v148, v118, v118
	v_mul_f32_e32 v149, v103, v103
	v_fmac_f32_e32 v149, v102, v102
	s_waitcnt lgkmcnt(0)
	v_mov_b32_e32 v147, v146
	s_nop 1
	v_permlane16_swap_b32_e32 v146, v147
	v_add_f32_e32 v146, v146, v147
	s_lshl_b32 s13, s73, 1
	s_add_i32 s13, s13, 0x3ffffff8
	s_waitcnt lgkmcnt(0)
	v_mov_b32_e32 v147, v146
	s_nop 1
	v_permlane32_swap_b32_e32 v146, v147
	v_add_f32_e32 v146, v146, v147
	v_mul_f32_e32 v147, v117, v117
	v_fmac_f32_e32 v147, v116, v116
	v_add_f32_e32 v147, v147, v148
	v_mul_f32_e32 v148, v113, v113
	v_fmac_f32_e32 v148, v112, v112
	v_add_f32_e32 v147, v147, v148
	v_mul_f32_e32 v148, v115, v115
	v_fmac_f32_e32 v148, v114, v114
	v_add_f32_e32 v147, v148, v147
	s_waitcnt lgkmcnt(0)
	v_mov_b32_e32 v148, v147
	s_nop 1
	v_permlane16_swap_b32_e32 v147, v148
	v_add_f32_e32 v147, v147, v148
	s_waitcnt lgkmcnt(0)
	v_mov_b32_e32 v148, v147
	s_nop 1
	v_permlane32_swap_b32_e32 v147, v148
	v_add_f32_e32 v147, v147, v148
	v_max3_f32 v146, v146, 0, v147
	v_mul_f32_e32 v147, v109, v109
	v_mul_f32_e32 v148, v111, v111
	v_fmac_f32_e32 v147, v108, v108
	v_fmac_f32_e32 v148, v110, v110
	v_add_f32_e32 v147, v147, v148
	v_mul_f32_e32 v148, v105, v105
	v_fmac_f32_e32 v148, v104, v104
	v_add_f32_e32 v147, v147, v148
	v_mul_f32_e32 v148, v107, v107
	v_fmac_f32_e32 v148, v106, v106
	v_add_f32_e32 v147, v148, v147
	s_waitcnt lgkmcnt(0)
	v_mov_b32_e32 v148, v147
	s_nop 1
	v_permlane16_swap_b32_e32 v147, v148
	v_add_f32_e32 v147, v147, v148
	s_waitcnt lgkmcnt(0)
	v_mov_b32_e32 v148, v147
	s_nop 1
	v_permlane32_swap_b32_e32 v147, v148
	v_add_f32_e32 v147, v147, v148
	v_mul_f32_e32 v148, v101, v101
	v_fmac_f32_e32 v148, v100, v100
	v_add_f32_e32 v148, v148, v149
	v_mul_f32_e32 v149, v97, v97
	v_fmac_f32_e32 v149, v96, v96
	v_add_f32_e32 v148, v148, v149
	v_mul_f32_e32 v149, v99, v99
	v_fmac_f32_e32 v149, v98, v98
	v_add_f32_e32 v148, v149, v148
	s_waitcnt lgkmcnt(0)
	v_mov_b32_e32 v149, v148
	s_nop 1
	v_permlane16_swap_b32_e32 v148, v149
	v_add_f32_e32 v148, v148, v149
	s_waitcnt lgkmcnt(0)
	v_mov_b32_e32 v149, v148
	s_nop 1
	v_permlane32_swap_b32_e32 v148, v149
	v_add_f32_e32 v148, v148, v149
	v_max3_f32 v146, v146, v147, v148
	v_mul_f32_e32 v147, v93, v93
	v_mul_f32_e32 v148, v95, v95
	v_fmac_f32_e32 v147, v92, v92
	v_fmac_f32_e32 v148, v94, v94
	v_add_f32_e32 v147, v147, v148
	v_mul_f32_e32 v148, v89, v89
	v_fmac_f32_e32 v148, v88, v88
	v_add_f32_e32 v147, v147, v148
	v_mul_f32_e32 v148, v91, v91
	v_fmac_f32_e32 v148, v90, v90
	v_add_f32_e32 v147, v148, v147
	v_mul_f32_e32 v149, v87, v87
	v_fmac_f32_e32 v149, v86, v86
	s_waitcnt lgkmcnt(0)
	v_mov_b32_e32 v148, v147
	s_nop 1
	v_permlane16_swap_b32_e32 v147, v148
	v_add_f32_e32 v147, v147, v148
	s_waitcnt lgkmcnt(0)
	v_mov_b32_e32 v148, v147
	s_nop 1
	v_permlane32_swap_b32_e32 v147, v148
	v_add_f32_e32 v147, v147, v148
	v_mul_f32_e32 v148, v85, v85
	v_fmac_f32_e32 v148, v84, v84
	v_add_f32_e32 v148, v148, v149
	v_mul_f32_e32 v149, v81, v81
	v_fmac_f32_e32 v149, v80, v80
	v_add_f32_e32 v148, v148, v149
	v_mul_f32_e32 v149, v83, v83
	v_fmac_f32_e32 v149, v82, v82
	v_add_f32_e32 v148, v149, v148
	s_waitcnt lgkmcnt(0)
	v_mov_b32_e32 v149, v148
	s_nop 1
	v_permlane16_swap_b32_e32 v148, v149
	v_add_f32_e32 v148, v148, v149
	s_waitcnt lgkmcnt(0)
	v_mov_b32_e32 v149, v148
	s_nop 1
	v_permlane32_swap_b32_e32 v148, v149
	v_add_f32_e32 v148, v148, v149
	v_max3_f32 v146, v146, v147, v148
	v_mul_f32_e32 v147, v77, v77
	v_mul_f32_e32 v148, v79, v79
	v_fmac_f32_e32 v147, v76, v76
	v_fmac_f32_e32 v148, v78, v78
	v_add_f32_e32 v147, v147, v148
	v_mul_f32_e32 v148, v73, v73
	v_fmac_f32_e32 v148, v72, v72
	v_add_f32_e32 v147, v147, v148
	v_mul_f32_e32 v148, v75, v75
	v_fmac_f32_e32 v148, v74, v74
	v_add_f32_e32 v147, v148, v147
	v_mul_f32_e32 v149, v63, v63
	v_fmac_f32_e32 v149, v62, v62
	s_waitcnt lgkmcnt(0)
	v_mov_b32_e32 v148, v147
	s_nop 1
	v_permlane16_swap_b32_e32 v147, v148
	v_add_f32_e32 v147, v147, v148
	s_waitcnt lgkmcnt(0)
	v_mov_b32_e32 v148, v147
	s_nop 1
	v_permlane32_swap_b32_e32 v147, v148
	v_add_f32_e32 v147, v147, v148
	v_mul_f32_e32 v148, v61, v61
	v_fmac_f32_e32 v148, v60, v60
	v_add_f32_e32 v148, v148, v149
	v_mul_f32_e32 v149, v53, v53
	v_fmac_f32_e32 v149, v52, v52
	v_add_f32_e32 v148, v148, v149
	v_mul_f32_e32 v149, v55, v55
	v_fmac_f32_e32 v149, v54, v54
	v_add_f32_e32 v148, v149, v148
	s_waitcnt lgkmcnt(0)
	v_mov_b32_e32 v149, v148
	s_nop 1
	v_permlane16_swap_b32_e32 v148, v149
	v_add_f32_e32 v148, v148, v149
	s_waitcnt lgkmcnt(0)
	v_mov_b32_e32 v149, v148
	s_nop 1
	v_permlane32_swap_b32_e32 v148, v149
	v_add_f32_e32 v148, v148, v149
	v_max3_f32 v146, v146, v147, v148
	ds_bpermute_b32 v147, v154, v146
	s_waitcnt lgkmcnt(0)
	v_max_f32_e32 v147, v147, v147
	v_max_f32_e32 v146, v146, v147
	ds_bpermute_b32 v147, v155, v146
	s_waitcnt lgkmcnt(0)
	v_max_f32_e32 v147, v147, v147
	v_max_f32_e32 v146, v146, v147
	ds_bpermute_b32 v147, v156, v146
	s_waitcnt lgkmcnt(0)
	v_max_f32_e32 v147, v147, v147
	v_max_f32_e32 v146, v146, v147
	ds_bpermute_b32 v147, v157, v146
	s_and_saveexec_b64 s[60:61], s[2:3]
	s_cbranch_execz .LBB0_209
	s_waitcnt lgkmcnt(0)
	v_max_f32_e32 v147, v147, v147
	v_max_f32_e32 v146, v146, v146
	s_mov_b64 s[66:67], exec
	v_max_f32_e32 v146, v146, v147
	s_mov_b32 s15, 0

;     __device__ __forceinline__ void operator()(const f32x4 (&acc)[2][2][4][2], const Unit& u, int wr, int wc, int fr, int fq) const {
;     ...
;             for (int bj = 0; bj < 2; ++bj) { float mx = 0.f;
; #pragma unroll
;                 for (int ai = 0; ai < 2; ++ai)
; #pragma unroll
;                     for (int m = 0; m < 4; ++m) { const f32x4 a = acc[ai][bj][m][0], c = acc[ai][bj][m][1];
;                         float s = (a[0] * a[0] + a[1] * a[1]) + (a[2] * a[2] + a[3] * a[3]) + (c[0] * c[0] + c[1] * c[1]) + (c[2] * c[2] + c[3] * c[3]);
;                         s += __builtin_bit_cast(float, __builtin_amdgcn_ds_bpermute((lane ^ 16) << 2, __builtin_bit_cast(int, s)));
;                         s += __builtin_bit_cast(float, __builtin_amdgcn_ds_bpermute((lane ^ 32) << 2, __builtin_bit_cast(int, s)));
;                         mx = fmaxf(mx, s); }
; #pragma unroll
;                 for (int x = 1; x < 16; x <<= 1) mx = fmaxf(mx, __builtin_bit_cast(float, __builtin_amdgcn_ds_bpermute((lane ^ x) << 2, __builtin_bit_cast(int, mx))));
;                 if (lane == 0) atomicMax(nrmk + (((u.pm >> 3) * 8 + 2 * (pn - 4) + bj) * 2 + (wc >> 1)) * 2 + (wc & 1), __float_as_uint(mx)); }
.LBB0_209:
	s_or_b64 exec, exec, s[60:61]
	v_mul_f32_e32 v146, v69, v69
	s_waitcnt lgkmcnt(0)
	v_mul_f32_e32 v147, v71, v71
	v_fmac_f32_e32 v146, v68, v68
	v_fmac_f32_e32 v147, v70, v70
	v_add_f32_e32 v146, v146, v147
	v_mul_f32_e32 v147, v65, v65
	v_fmac_f32_e32 v147, v64, v64
	v_add_f32_e32 v146, v146, v147
	v_mul_f32_e32 v147, v67, v67
	v_fmac_f32_e32 v147, v66, v66
	v_add_f32_e32 v146, v147, v146
	v_mul_f32_e32 v148, v59, v59
	v_fmac_f32_e32 v148, v58, v58
	v_mul_f32_e32 v149, v39, v39
	v_fmac_f32_e32 v149, v38, v38
	s_waitcnt lgkmcnt(0)
	v_mov_b32_e32 v147, v146
	s_nop 1
	v_permlane16_swap_b32_e32 v146, v147
	v_add_f32_e32 v146, v146, v147
	s_waitcnt lgkmcnt(0)
	v_mov_b32_e32 v147, v146
	s_nop 1
	v_permlane32_swap_b32_e32 v146, v147
	v_add_f32_e32 v146, v146, v147
	v_mul_f32_e32 v147, v57, v57
	v_fmac_f32_e32 v147, v56, v56
	v_add_f32_e32 v147, v147, v148
	v_mul_f32_e32 v148, v49, v49
	v_fmac_f32_e32 v148, v48, v48
	v_add_f32_e32 v147, v147, v148
	v_mul_f32_e32 v148, v51, v51
	v_fmac_f32_e32 v148, v50, v50
	v_add_f32_e32 v147, v148, v147
	s_waitcnt lgkmcnt(0)
	v_mov_b32_e32 v148, v147
	s_nop 1
	v_permlane16_swap_b32_e32 v147, v148
	v_add_f32_e32 v147, v147, v148
	s_waitcnt lgkmcnt(0)
	v_mov_b32_e32 v148, v147
	s_nop 1
	v_permlane32_swap_b32_e32 v147, v148
	v_add_f32_e32 v147, v147, v148
	v_max3_f32 v146, v146, 0, v147
	v_mul_f32_e32 v147, v45, v45
	v_mul_f32_e32 v148, v47, v47
	v_fmac_f32_e32 v147, v44, v44
	v_fmac_f32_e32 v148, v46, v46
	v_add_f32_e32 v147, v147, v148
	v_mul_f32_e32 v148, v41, v41
	v_fmac_f32_e32 v148, v40, v40
	v_add_f32_e32 v147, v147, v148
	v_mul_f32_e32 v148, v43, v43
	v_fmac_f32_e32 v148, v42, v42
	v_add_f32_e32 v147, v148, v147
	s_waitcnt lgkmcnt(0)
	v_mov_b32_e32 v148, v147
	s_nop 1
	v_permlane16_swap_b32_e32 v147, v148
	v_add_f32_e32 v147, v147, v148
	s_waitcnt lgkmcnt(0)
	v_mov_b32_e32 v148, v147
	s_nop 1
	v_permlane32_swap_b32_e32 v147, v148
	v_add_f32_e32 v147, v147, v148
	v_mul_f32_e32 v148, v37, v37
	v_fmac_f32_e32 v148, v36, v36
	v_add_f32_e32 v148, v148, v149
	v_mul_f32_e32 v149, v33, v33
	v_fmac_f32_e32 v149, v32, v32
	v_add_f32_e32 v148, v148, v149
	v_mul_f32_e32 v149, v35, v35
	v_fmac_f32_e32 v149, v34, v34
	v_add_f32_e32 v148, v149, v148
	s_waitcnt lgkmcnt(0)
	v_mov_b32_e32 v149, v148
	s_nop 1
	v_permlane16_swap_b32_e32 v148, v149
	v_add_f32_e32 v148, v148, v149
	s_waitcnt lgkmcnt(0)
	v_mov_b32_e32 v149, v148
	s_nop 1
	v_permlane32_swap_b32_e32 v148, v149
	v_add_f32_e32 v148, v148, v149
	v_max3_f32 v146, v146, v147, v148
	v_mul_f32_e32 v147, v29, v29
	v_mul_f32_e32 v148, v31, v31
	v_fmac_f32_e32 v147, v28, v28
	v_fmac_f32_e32 v148, v30, v30
	v_add_f32_e32 v147, v147, v148
	v_mul_f32_e32 v148, v25, v25
	v_fmac_f32_e32 v148, v24, v24
	v_add_f32_e32 v147, v147, v148
	v_mul_f32_e32 v148, v27, v27
	v_fmac_f32_e32 v148, v26, v26
	v_add_f32_e32 v147, v148, v147
	v_mul_f32_e32 v149, v23, v23
	v_fmac_f32_e32 v149, v22, v22
	s_waitcnt lgkmcnt(0)
	v_mov_b32_e32 v148, v147
	s_nop 1
	v_permlane16_swap_b32_e32 v147, v148
	v_add_f32_e32 v147, v147, v148
	s_waitcnt lgkmcnt(0)
	v_mov_b32_e32 v148, v147
	s_nop 1
	v_permlane32_swap_b32_e32 v147, v148
	v_add_f32_e32 v147, v147, v148
	v_mul_f32_e32 v148, v21, v21
	v_fmac_f32_e32 v148, v20, v20
	v_add_f32_e32 v148, v148, v149
	v_mul_f32_e32 v149, v17, v17
	v_fmac_f32_e32 v149, v16, v16
	v_add_f32_e32 v148, v148, v149
	v_mul_f32_e32 v149, v19, v19
	v_fmac_f32_e32 v149, v18, v18
	v_add_f32_e32 v148, v149, v148
	s_waitcnt lgkmcnt(0)
	v_mov_b32_e32 v149, v148
	s_nop 1
	v_permlane16_swap_b32_e32 v148, v149
	v_add_f32_e32 v148, v148, v149
	s_waitcnt lgkmcnt(0)
	v_mov_b32_e32 v149, v148
	s_nop 1
	v_permlane32_swap_b32_e32 v148, v149
	v_add_f32_e32 v148, v148, v149
	v_max3_f32 v146, v146, v147, v148
	v_mul_f32_e32 v147, v13, v13
	v_mul_f32_e32 v148, v15, v15
	v_fmac_f32_e32 v147, v12, v12
	v_fmac_f32_e32 v148, v14, v14
	v_add_f32_e32 v147, v147, v148
	v_mul_f32_e32 v148, v9, v9
	v_fmac_f32_e32 v148, v8, v8
	v_add_f32_e32 v147, v147, v148
	v_mul_f32_e32 v148, v11, v11
	v_fmac_f32_e32 v148, v10, v10
	v_add_f32_e32 v147, v148, v147
	v_mul_f32_e32 v149, v7, v7
	v_fmac_f32_e32 v149, v6, v6
	s_waitcnt lgkmcnt(0)
	v_mov_b32_e32 v148, v147
	s_nop 1
	v_permlane16_swap_b32_e32 v147, v148
	v_add_f32_e32 v147, v147, v148
	s_waitcnt lgkmcnt(0)
	v_mov_b32_e32 v148, v147
	s_nop 1
	v_permlane32_swap_b32_e32 v147, v148
	v_add_f32_e32 v147, v147, v148
	v_mul_f32_e32 v148, v5, v5
	v_fmac_f32_e32 v148, v4, v4
	v_add_f32_e32 v148, v148, v149
	v_mul_f32_e32 v149, v1, v1
	v_fmac_f32_e32 v149, v0, v0
	v_add_f32_e32 v148, v148, v149
	v_mul_f32_e32 v149, v3, v3
	v_fmac_f32_e32 v149, v2, v2
	v_add_f32_e32 v148, v149, v148
	s_waitcnt lgkmcnt(0)
	v_mov_b32_e32 v149, v148
	s_nop 1
	v_permlane16_swap_b32_e32 v148, v149
	v_add_f32_e32 v148, v148, v149
	s_waitcnt lgkmcnt(0)
	v_mov_b32_e32 v149, v148
	s_nop 1
	v_permlane32_swap_b32_e32 v148, v149
	v_add_f32_e32 v148, v148, v149
	v_max3_f32 v146, v146, v147, v148
	ds_bpermute_b32 v147, v154, v146
	s_waitcnt lgkmcnt(0)
	v_max_f32_e32 v147, v147, v147
	v_max_f32_e32 v146, v146, v147
	ds_bpermute_b32 v147, v155, v146
	s_waitcnt lgkmcnt(0)
	v_max_f32_e32 v147, v147, v147
	v_max_f32_e32 v146, v146, v147
	ds_bpermute_b32 v147, v156, v146
	s_waitcnt lgkmcnt(0)
	v_max_f32_e32 v147, v147, v147
	v_max_f32_e32 v146, v146, v147
	ds_bpermute_b32 v147, v157, v146
	s_and_saveexec_b64 s[60:61], s[2:3]
	s_cbranch_execz .LBB0_214
	s_waitcnt lgkmcnt(0)
	v_max_f32_e32 v147, v147, v147
	v_max_f32_e32 v146, v146, v146
	s_mov_b64 s[66:67], exec
	v_max_f32_e32 v146, v146, v147
	s_mov_b32 s15, 0
